# Residual-add GEMM epilogue: first four x loads of the second half issued with the first half's loads (spare registers), their staged waits dropped
# speedup vs baseline: 1.0007x; 1.0007x over previous
.LBB0_633:
	s_and_b64 vcc, exec, s[6:7]
	s_cbranch_vccz .LBB0_652
	s_cmp_eq_u32 s47, 2
	s_mov_b64 s[74:75], -1
	s_cbranch_scc0 .LBB0_652
	s_lshl_b32 s74, s15, 8
	s_lshl_b32 s1, s48, 8
	s_ashr_i32 s75, s74, 31
	s_or_b32 s1, s1, s58
	s_lshl_b64 s[6:7], s[74:75], 11
	v_lshl_add_u32 v128, v221, 3, s1
	s_add_u32 s6, s76, s6
	s_addc_u32 s7, s77, s7
	s_waitcnt lgkmcnt(0)
	v_ashrrev_i32_e32 v129, 31, v128
	v_ashrrev_i32_e32 v171, 31, v170
	v_lshl_add_u64 v[152:153], v[128:129], 1, s[6:7]
	v_lshlrev_b64 v[128:129], 11, v[170:171]
	v_lshl_add_u64 v[184:185], v[152:153], 0, v[128:129]
	global_load_dwordx4 v[176:179], v[184:185], off
	global_load_dwordx4 v[180:183], v[184:185], off offset:256
	s_mov_b32 s1, 0x8000
	v_add_co_u32_e32 v128, vcc, s1, v184
	s_mov_b32 s1, 0x10000
	s_nop 0
	v_addc_co_u32_e32 v129, vcc, 0, v185, vcc
	v_add_co_u32_e32 v130, vcc, s1, v184
	s_mov_b64 s[6:7], 0x8000
	s_nop 0
	v_addc_co_u32_e32 v131, vcc, 0, v185, vcc
	s_mov_b32 s1, 0x18000
	v_lshl_add_u64 v[172:173], v[184:185], 0, s[6:7]
	s_mov_b64 s[6:7], 0x10000
	v_add_co_u32_e32 v132, vcc, s1, v184
	v_lshl_add_u64 v[174:175], v[184:185], 0, s[6:7]
	s_mov_b64 s[6:7], 0x18000
	v_addc_co_u32_e32 v133, vcc, 0, v185, vcc
	v_lshl_add_u64 v[154:155], v[184:185], 0, s[6:7]
	global_load_dwordx4 v[148:151], v[128:129], off
	global_load_dwordx4 v[144:147], v[172:173], off offset:256
	global_load_dwordx4 v[136:139], v[174:175], off offset:256
	global_load_dwordx4 v[140:143], v[130:131], off
	s_nop 0
	global_load_dwordx4 v[132:135], v[132:133], off
	s_nop 0
	global_load_dwordx4 v[128:131], v[154:155], off offset:256
	s_mov_b64 s[34:35], 0x40000
	v_lshl_add_u64 v[246:247], v[184:185], 0, s[34:35]
	global_load_dwordx4 v[230:233], v[246:247], off
	global_load_dwordx4 v[234:237], v[246:247], off offset:256
	s_mov_b64 s[34:35], 0x48000
	v_lshl_add_u64 v[246:247], v[184:185], 0, s[34:35]
	global_load_dwordx4 v[238:241], v[246:247], off
	global_load_dwordx4 v[242:245], v[246:247], off offset:256
	v_cmp_eq_u32_e64 s[6:7], 0, v221
	s_waitcnt vmcnt(0)
	v_lshlrev_b32_e32 v188, 16, v176
	v_and_b32_e32 v189, 0xffff0000, v176
	v_lshlrev_b32_e32 v176, 16, v177
	v_and_b32_e32 v177, 0xffff0000, v177
	v_lshlrev_b32_e32 v190, 16, v178
	v_and_b32_e32 v191, 0xffff0000, v178
	v_lshlrev_b32_e32 v178, 16, v179
	v_and_b32_e32 v179, 0xffff0000, v179
	v_lshlrev_b32_e32 v192, 16, v180
	v_and_b32_e32 v193, 0xffff0000, v180
	v_lshlrev_b32_e32 v180, 16, v181
	v_and_b32_e32 v181, 0xffff0000, v181
	v_lshlrev_b32_e32 v222, 16, v182
	v_and_b32_e32 v223, 0xffff0000, v182
	v_lshlrev_b32_e32 v182, 16, v183
	v_and_b32_e32 v183, 0xffff0000, v183
	v_pk_fma_f32 v[224:225], s[90:91], v[122:123], v[176:177]
	v_pk_fma_f32 v[188:189], s[86:87], v[120:121], v[188:189]
	v_pk_fma_f32 v[226:227], s[90:91], v[114:115], v[178:179]
	v_pk_fma_f32 v[178:179], s[86:87], v[112:113], v[190:191]
	v_pk_fma_f32 v[180:181], s[90:91], v[126:127], v[180:181]
	v_pk_fma_f32 v[190:191], s[86:87], v[124:125], v[192:193]
	v_pk_fma_f32 v[182:183], s[90:91], v[118:119], v[182:183]
	v_pk_fma_f32 v[192:193], s[86:87], v[116:117], v[222:223]
	v_mul_f32_e32 v156, v189, v189
	v_mul_f32_e32 v187, v225, v225
	v_mul_f32_e32 v222, v179, v179
	v_mul_f32_e32 v223, v227, v227
	v_cvt_pk_bf16_f32 v176, v188, v189
	v_cvt_pk_bf16_f32 v177, v224, v225
	v_mul_f32_e32 v189, v191, v191
	v_mul_f32_e32 v225, v181, v181
	v_mul_f32_e32 v228, v193, v193
	v_mul_f32_e32 v229, v183, v183
	v_fmac_f32_e32 v156, v188, v188
	v_fmac_f32_e32 v187, v224, v224
	v_fmac_f32_e32 v222, v178, v178
	v_fmac_f32_e32 v223, v226, v226
	v_fmac_f32_e32 v189, v190, v190
	v_fmac_f32_e32 v225, v180, v180
	v_fmac_f32_e32 v228, v192, v192
	v_fmac_f32_e32 v229, v182, v182
	v_add_f32_e32 v156, v156, v187
	v_add_f32_e32 v187, v222, v223
	v_add_f32_e32 v188, v189, v225
	v_add_f32_e32 v189, v228, v229
	v_add_f32_e32 v156, v156, v187
	v_add_f32_e32 v187, v188, v189
	v_add_f32_e32 v156, v156, v187
	ds_bpermute_b32 v187, v218, v156
	v_cvt_pk_bf16_f32 v178, v178, v179
	v_cvt_pk_bf16_f32 v179, v226, v227
	global_store_dwordx4 v[184:185], v[176:179], off
	s_waitcnt lgkmcnt(0)
	v_add_f32_e32 v156, v156, v187
	ds_bpermute_b32 v176, v219, v156
	v_cvt_pk_bf16_f32 v178, v190, v191
	v_cvt_pk_bf16_f32 v179, v180, v181
	v_cvt_pk_bf16_f32 v180, v192, v193
	v_cvt_pk_bf16_f32 v181, v182, v183
	global_store_dwordx4 v[184:185], v[178:181], off offset:256
	s_and_saveexec_b64 vcc, s[6:7]
	s_cbranch_execz .LBB0_637
	s_waitcnt lgkmcnt(0)
	v_add_f32_e32 v156, v156, v176
	v_mul_f32_e32 v156, 0x4b800000, v156
	v_trunc_f32_e32 v156, v156
	v_mul_f32_e32 v176, 0x2f800000, v156
	v_floor_f32_e32 v177, v176
	v_fmac_f32_e32 v156, 0xcf800000, v177
	v_cvt_u32_f32_e32 v176, v156
	v_cvt_u32_f32_e32 v177, v177
	v_add_u32_e32 v178, s74, v170
	v_ashrrev_i32_e32 v179, 31, v178
	v_lshl_add_u64 v[178:179], v[178:179], 3, s[78:79]
	global_atomic_add_x2 v[178:179], v[176:177], off

.LBB0_643:
	s_or_b64 exec, exec, s[74:75]
	s_waitcnt lgkmcnt(0)
	v_lshlrev_b64 v[128:129], 11, v[170:171]
	v_lshl_add_u64 v[128:129], v[152:153], 0, v[128:129]
	v_add_co_u32_e32 v188, vcc, 0x40000, v128
	s_mov_b64 s[34:35], 0x40000
	s_nop 0
	v_addc_co_u32_e32 v189, vcc, 0, v129, vcc
	v_lshl_add_u64 v[180:181], v[128:129], 0, s[34:35]
	v_mov_b32_e32 v182, v230
	v_mov_b32_e32 v183, v231
	v_mov_b32_e32 v184, v232
	v_mov_b32_e32 v185, v233
	v_mov_b32_e32 v152, v234
	v_mov_b32_e32 v153, v235
	v_mov_b32_e32 v154, v236
	v_mov_b32_e32 v155, v237
	v_add_co_u32_e32 v130, vcc, 0x48000, v128
	s_mov_b64 s[34:35], 0x48000
	s_nop 0
	v_addc_co_u32_e32 v131, vcc, 0, v129, vcc
	v_lshl_add_u64 v[178:179], v[128:129], 0, s[34:35]
	v_mov_b32_e32 v148, v238
	v_mov_b32_e32 v149, v239
	v_mov_b32_e32 v150, v240
	v_mov_b32_e32 v151, v241
	v_mov_b32_e32 v144, v242
	v_mov_b32_e32 v145, v243
	v_mov_b32_e32 v146, v244
	v_mov_b32_e32 v147, v245
	s_mov_b64 s[34:35], 0x50000
	v_add_co_u32_e32 v130, vcc, 0x50000, v128
	v_lshl_add_u64 v[176:177], v[128:129], 0, s[34:35]
	s_nop 0
	v_addc_co_u32_e32 v131, vcc, 0, v129, vcc
	s_mov_b64 s[34:35], 0x58000
	v_lshl_add_u64 v[174:175], v[128:129], 0, s[34:35]
	v_add_co_u32_e32 v128, vcc, 0x58000, v128
	global_load_dwordx4 v[140:143], v[130:131], off
	global_load_dwordx4 v[136:139], v[176:177], off offset:256
	v_addc_co_u32_e32 v129, vcc, 0, v129, vcc
	global_load_dwordx4 v[132:135], v[128:129], off
	s_nop 0
	global_load_dwordx4 v[128:131], v[174:175], off offset:256
	v_lshlrev_b32_e32 v190, 16, v182
	v_and_b32_e32 v191, 0xffff0000, v182
	v_lshlrev_b32_e32 v182, 16, v183
	v_and_b32_e32 v183, 0xffff0000, v183
	v_pk_fma_f32 v[222:223], s[90:91], v[58:59], v[182:183]
	v_pk_fma_f32 v[182:183], s[86:87], v[56:57], v[190:191]
	v_lshlrev_b32_e32 v192, 16, v184
	v_and_b32_e32 v193, 0xffff0000, v184
	v_lshlrev_b32_e32 v184, 16, v185
	v_and_b32_e32 v185, 0xffff0000, v185
	v_mul_f32_e32 v156, v183, v183
	v_mul_f32_e32 v171, v223, v223
	v_pk_fma_f32 v[190:191], s[90:91], v[50:51], v[184:185]
	v_pk_fma_f32 v[184:185], s[86:87], v[48:49], v[192:193]
	v_fmac_f32_e32 v156, v182, v182
	v_fmac_f32_e32 v171, v222, v222
	v_add_f32_e32 v156, v156, v171
	v_mul_f32_e32 v171, v185, v185
	v_mul_f32_e32 v187, v191, v191
	v_cvt_pk_bf16_f32 v182, v182, v183
	v_cvt_pk_bf16_f32 v183, v222, v223
	v_fmac_f32_e32 v171, v184, v184
	v_fmac_f32_e32 v187, v190, v190
	v_cvt_pk_bf16_f32 v184, v184, v185
	v_cvt_pk_bf16_f32 v185, v190, v191
	global_store_dwordx4 v[188:189], v[182:185], off
	v_add_f32_e32 v171, v171, v187
	v_add_f32_e32 v156, v156, v171
	v_lshlrev_b32_e32 v182, 16, v152
	v_and_b32_e32 v183, 0xffff0000, v152
	v_lshlrev_b32_e32 v152, 16, v153
	v_and_b32_e32 v153, 0xffff0000, v153
	v_lshlrev_b32_e32 v184, 16, v154
	v_and_b32_e32 v185, 0xffff0000, v154
	v_lshlrev_b32_e32 v154, 16, v155
	v_and_b32_e32 v155, 0xffff0000, v155
	v_pk_fma_f32 v[188:189], s[90:91], v[62:63], v[152:153]
	v_pk_fma_f32 v[152:153], s[86:87], v[60:61], v[182:183]
	v_pk_fma_f32 v[182:183], s[90:91], v[54:55], v[154:155]
	v_pk_fma_f32 v[154:155], s[86:87], v[52:53], v[184:185]
	v_mul_f32_e32 v171, v153, v153
	v_mul_f32_e32 v184, v189, v189
	v_fmac_f32_e32 v171, v152, v152
	v_fmac_f32_e32 v184, v188, v188
	v_add_f32_e32 v171, v171, v184
	v_mul_f32_e32 v184, v155, v155
	v_mul_f32_e32 v185, v183, v183
	v_fmac_f32_e32 v184, v154, v154
	v_fmac_f32_e32 v185, v182, v182
	v_add_f32_e32 v184, v184, v185
	v_add_f32_e32 v171, v171, v184
	v_add_f32_e32 v156, v156, v171
	v_cvt_pk_bf16_f32 v152, v152, v153
	v_cvt_pk_bf16_f32 v153, v188, v189
	v_cvt_pk_bf16_f32 v154, v154, v155
	v_cvt_pk_bf16_f32 v155, v182, v183
	global_store_dwordx4 v[180:181], v[152:155], off offset:256
	ds_bpermute_b32 v152, v218, v156
	s_waitcnt lgkmcnt(0)
	v_add_f32_e32 v152, v156, v152
	ds_bpermute_b32 v153, v219, v152
	s_and_saveexec_b64 s[74:75], s[6:7]
	s_cbranch_execz .LBB0_645
	s_waitcnt lgkmcnt(0)
	v_add_f32_e32 v152, v152, v153
	v_mul_f32_e32 v152, 0x4b800000, v152
	v_trunc_f32_e32 v152, v152
	v_mul_f32_e32 v153, 0x2f800000, v152
	v_floor_f32_e32 v153, v153
	v_fmac_f32_e32 v152, 0xcf800000, v153
	v_cvt_u32_f32_e32 v152, v152
	v_cvt_u32_f32_e32 v153, v153
	global_atomic_add_x2 v[172:173], v[152:153], off offset:1024
.LBB0_645:
	s_or_b64 exec, exec, s[74:75]
	v_lshlrev_b32_e32 v152, 16, v148
	s_waitcnt lgkmcnt(0)
	v_and_b32_e32 v153, 0xffff0000, v148
	v_lshlrev_b32_e32 v148, 16, v149
	v_and_b32_e32 v149, 0xffff0000, v149
	v_lshlrev_b32_e32 v154, 16, v150
	v_and_b32_e32 v155, 0xffff0000, v150
	v_lshlrev_b32_e32 v150, 16, v151
	v_and_b32_e32 v151, 0xffff0000, v151
	v_pk_fma_f32 v[180:181], s[90:91], v[42:43], v[148:149]
	v_pk_fma_f32 v[148:149], s[86:87], v[40:41], v[152:153]
	v_pk_fma_f32 v[152:153], s[90:91], v[34:35], v[150:151]
	v_pk_fma_f32 v[150:151], s[86:87], v[32:33], v[154:155]
	v_mul_f32_e32 v154, v149, v149
	v_mul_f32_e32 v155, v181, v181
	v_fmac_f32_e32 v154, v148, v148
	v_fmac_f32_e32 v155, v180, v180
	v_add_f32_e32 v154, v154, v155
	v_mul_f32_e32 v155, v151, v151
	v_cvt_pk_bf16_f32 v148, v148, v149
	v_cvt_pk_bf16_f32 v149, v180, v181
	v_fmac_f32_e32 v155, v150, v150
	v_mul_f32_e32 v156, v153, v153
	v_cvt_pk_bf16_f32 v150, v150, v151
	v_cvt_pk_bf16_f32 v151, v152, v153
	global_store_dwordx4 v[178:179], v[148:151], off
	v_fmac_f32_e32 v156, v152, v152
	v_add_f32_e32 v155, v155, v156
	v_lshlrev_b32_e32 v148, 16, v144
	v_and_b32_e32 v149, 0xffff0000, v144
	v_lshlrev_b32_e32 v144, 16, v145
	v_and_b32_e32 v145, 0xffff0000, v145
	v_lshlrev_b32_e32 v150, 16, v146
	v_and_b32_e32 v151, 0xffff0000, v146
	v_lshlrev_b32_e32 v146, 16, v147
	v_and_b32_e32 v147, 0xffff0000, v147
	v_pk_fma_f32 v[152:153], s[90:91], v[46:47], v[144:145]
	v_pk_fma_f32 v[144:145], s[86:87], v[44:45], v[148:149]
	v_pk_fma_f32 v[148:149], s[90:91], v[38:39], v[146:147]
	v_pk_fma_f32 v[146:147], s[86:87], v[36:37], v[150:151]
	v_mul_f32_e32 v150, v145, v145
	v_mul_f32_e32 v151, v153, v153
	v_fmac_f32_e32 v150, v144, v144
	v_fmac_f32_e32 v151, v152, v152
	v_add_f32_e32 v154, v154, v155
	v_add_f32_e32 v150, v150, v151
	v_mul_f32_e32 v151, v147, v147
	v_mul_f32_e32 v155, v149, v149
	v_fmac_f32_e32 v151, v146, v146
	v_fmac_f32_e32 v155, v148, v148
	v_add_f32_e32 v151, v151, v155
	v_add_f32_e32 v150, v150, v151
	v_add_f32_e32 v150, v154, v150
	v_cvt_pk_bf16_f32 v144, v144, v145
	v_cvt_pk_bf16_f32 v145, v152, v153
	v_cvt_pk_bf16_f32 v146, v146, v147
	v_cvt_pk_bf16_f32 v147, v148, v149
	global_store_dwordx4 v[178:179], v[144:147], off offset:256
	ds_bpermute_b32 v144, v218, v150
	s_waitcnt lgkmcnt(0)
	v_add_f32_e32 v144, v150, v144
	ds_bpermute_b32 v145, v219, v144
	s_and_saveexec_b64 s[74:75], s[6:7]
	s_cbranch_execz .LBB0_647
	s_waitcnt lgkmcnt(0)
	v_add_f32_e32 v144, v144, v145
	v_mul_f32_e32 v144, 0x4b800000, v144
	v_trunc_f32_e32 v144, v144
	v_mul_f32_e32 v145, 0x2f800000, v144
	v_floor_f32_e32 v145, v145
	v_fmac_f32_e32 v144, 0xcf800000, v145
	v_cvt_u32_f32_e32 v144, v144
	v_cvt_u32_f32_e32 v145, v145
	global_atomic_add_x2 v[172:173], v[144:145], off offset:1152
